# static s_setprio 1 for waves 4-7 during the attention phase (asm guide 7.4) on top of v37
# speedup vs baseline: 1.0072x; 1.0003x over previous
; #define LAS __attribute__((address_space(3)))
;     __device__ __forceinline__ const float* in(int i) const { return (const float*)(const __attribute__((address_space(1))) float*)ld(i); }
; __device__ __forceinline__ void phase_attn(const DArgs& a, LAS unsigned char* lds) {
;     const int tid = threadIdx.x, wave = tid >> 6, lane = tid & 63, fr = lane & 15, g = lane >> 4;
;     const bf16_t* qk = (const bf16_t*)(a.wsp() + W_QK); const bf16_t* vT = (const bf16_t*)(a.wsp() + W_VT);
;     const bf16_t* Ks = (const bf16_t*)(a.wsp() + W_KS); const bf16_t* VsT = (const bf16_t*)(a.wsp() + W_VST);
;     const float* relb = a.in(I_RELB);
;     bf16_t* oatt = (bf16_t*)(a.wsp() + W_MIX);
;     LAS float* biasT = (LAS float*)(lds + A_B);
;     const float scale = 0.08838834764831845f;
;     constexpr int NITEMS = 2048 + 128;
;     struct Item { int h, qrow, qpos, tile_lo, tile_hi, qc, nkeys, ldk, ldv, kpos_base; const bf16_t* Kb; const bf16_t* Vb; bool wact, prompt; };
;     auto setup = [&](int it) -> Item { Item I; I.prompt = it < 2048; I.qc = 0;
;         if (I.prompt) { const int pi = it >> 4; I.h = it & 15; I.qc = 2 * pi + (wave >> 2); I.qrow = I.qc * 64 + (wave & 3) * 16 + fr; I.qpos = I.qrow;
;             I.tile_lo = 2 * pi - 8 < 0 ? 0 : 2 * pi - 8; I.tile_hi = 2 * pi + 1; I.nkeys = 1 << 30; I.ldk = 4096; I.ldv = TA; I.kpos_base = 0;
;             I.Kb = qk + 2048 + I.h * 128; I.Vb = vT + (size_t)(I.h * 128) * TA; I.wact = true; }
;         else { const int s_ = it - 2048, b = s_ >> 4; I.h = s_ & 15; const int w2 = wave & 1; I.qrow = TP + b * 32 + w2 * 16 + fr; I.qpos = 2048 + w2 * 16 + fr;
;             I.tile_lo = 0; I.tile_hi = 8; I.nkeys = 544; I.ldk = D; I.ldv = 576; I.kpos_base = 1536;
;             I.Kb = Ks + (size_t)b * 576 * D + I.h * 128; I.Vb = VsT + ((size_t)b * D + I.h * 128) * 576; I.wact = wave < 2; }
;         return I; };
;     u32x4 kreg[2], vreg[2];
;     const int kr = tid >> 4, kc = tid & 15, vr = tid >> 3, vc = tid & 7;
;     ...
;     if ((int)blockIdx.x >= NITEMS) return;
;     Item cur = setup(blockIdx.x);
;     bf16x8 qf[4], qfn[4];
;     float biasn = tid < 257 ? relb[cur.h * 257 + tid] : 0.f;
;     ATT_LOADQ(qf, cur);
;     ATT_LOAD(cur, cur.tile_lo);
; __global__ __launch_bounds__(512, 2) void mega(Args aa) {
;     ...
;     PH(16) { phase_attn(a, lds); }
.LBB0_1355:
	s_cmp_lt_i32 s78, 17
	s_cselect_b64 s[6:7], -1, 0
	s_and_b64 s[0:1], s[6:7], s[0:1]
	s_andn2_b64 vcc, exec, s[0:1]
	s_cbranch_vccnz .LBB0_1397
	s_mov_b32 s101, 0xa000
	v_lshrrev_b32_e32 v253, 8, v166
	s_nop 0
	v_readfirstlane_b32 s100, v253
	s_cmp_eq_u32 s100, 1
	s_cbranch_scc0 .Lattn_prio_skip
	s_setprio 1
.Lattn_prio_skip:
	s_add_i32 s0, 0, 0x200e0
	s_add_i32 s1, 0, 0x20108
	v_mov_b32_e32 v0, s1
	v_mov_b32_e32 v2, s0
	ds_read_b64 v[0:1], v0
	ds_read_b64 v[2:3], v2
	s_cmpk_gt_i32 s2, 0x87f
	s_waitcnt lgkmcnt(1)
	v_readfirstlane_b32 s24, v1
	v_readfirstlane_b32 s25, v0
	s_waitcnt lgkmcnt(0)
	v_readfirstlane_b32 s9, v3
	v_readfirstlane_b32 s8, v2
	s_cbranch_scc1 .LBB0_1397
	s_cmpk_lt_i32 s2, 0x800
	s_cselect_b64 s[14:15], -1, 0
	s_and_b32 s54, s2, 15
	s_lshl_b32 s20, s54, 7
	s_add_u32 s48, s25, 0x1ce58000
	s_addc_u32 s49, s24, 0
	s_add_u32 s50, s25, 0x20f58000
	s_addc_u32 s51, s24, 0
	s_add_u32 s52, s25, 0x22158000
	v_lshrrev_b32_e32 v0, 2, v166
	v_and_b32_e32 v33, 15, v166
	s_addc_u32 s53, s24, 0
	v_and_b32_e32 v1, 16, v0
	s_movk_i32 s0, 0x80
	s_movk_i32 s59, 0x800
	s_cmpk_gt_i32 s2, 0x7ff
	v_or_b32_e32 v34, v33, v1
	v_cmp_gt_u32_e64 s[10:11], s0, v166
	s_mov_b32 s61, 8
	s_cbranch_scc0 .LBB0_1359
	s_add_i32 s0, s2, 0xfffff800
	s_lshr_b32 s0, s0, 4
	s_lshl_b32 s1, s0, 5
	s_addk_i32 s1, 0x4000
	v_or3_b32 v98, s1, v1, v33
	s_mov_b32 s1, 0
	s_mul_hi_u32 s4, s0, 0x240000
	s_mul_i32 s5, s0, 0x240000
	s_lshl_b64 s[0:1], s[0:1], 11
	s_or_b32 s0, s0, s20
	s_mulk_i32 s1, 0x480
	s_mul_hi_u32 s16, s0, 0x480
	s_add_i32 s16, s16, s1
	s_add_u32 s18, s50, s5
	s_mulk_i32 s0, 0x480
	s_addc_u32 s19, s51, s4
	s_add_u32 s0, s52, s0
	s_addc_u32 s1, s53, s16
	s_mov_b64 s[4:5], 0
	s_branch .LBB0_1360

; __device__ __forceinline__ unsigned xb_ld(unsigned* p)              { return __hip_atomic_load(p, __ATOMIC_RELAXED, __HIP_MEMORY_SCOPE_AGENT); }
; __device__ __forceinline__ void xcd_barrier_complete(unsigned* bar, unsigned x, unsigned& nloc, unsigned& nx) {
;     const unsigned G = gridDim.x * gridDim.y * gridDim.z;
;     unsigned sum, cnt, mine, sp = 0u;
;     for (;;) {
;         sum = 0u; cnt = 0u; mine = 0u;
; #pragma unroll
;         for (unsigned j = 0; j < 16; ++j) { const unsigned c = xb_ld(&bar[XB_XCNT(j)]); sum += c; cnt += (c > 0u) ? 1u : 0u; mine = (j == x) ? c : mine; }
; __device__ __forceinline__ void xcd_barrier(const XcdBarrier& b) {
;     asm volatile("s_waitcnt vmcnt(0)" ::: "memory");
;     __syncthreads();
;     if (threadIdx.x == 0) {
;         unsigned* bar = b.bar;
;         __builtin_amdgcn_s_waitcnt(0);
;         unsigned nloc = b.st[0], nx = b.st[1];
;         if (nloc == 0u) { xcd_barrier_complete(bar, b.x, nloc, nx); b.st[0] = nloc; b.st[1] = nx; }
.LBB0_1397:
	s_setprio 0
	s_cmp_gt_i32 s79, 17
	s_cselect_b64 s[4:5], -1, 0
	s_and_b64 s[0:1], s[6:7], s[4:5]
	s_andn2_b64 vcc, exec, s[0:1]
	s_cbranch_vccnz .LBB0_1451
	s_waitcnt vmcnt(0)
	s_barrier
	s_and_saveexec_b64 s[0:1], s[12:13]
	s_cbranch_execz .LBB0_1450
	s_add_i32 s6, 0, 0x201c0
	v_mov_b32_e32 v0, s6
	s_waitcnt vmcnt(0) expcnt(0) lgkmcnt(0)
	ds_read_b32 v2, v0
	s_add_i32 s6, 0, 0x201c4
	v_mov_b32_e32 v0, s6
	ds_read_b32 v0, v0
	s_waitcnt lgkmcnt(1)
	v_cmp_ne_u32_e32 vcc, 0, v2
	s_cbranch_vccnz .LBB0_1414
	v_readlane_b32 s6, v254, 0
	s_mul_i32 s33, s77, s6
	s_add_u32 s6, s80, 0x29978200
	s_addc_u32 s7, s81, 0
	s_add_u32 s8, s80, 0x29978400
	s_addc_u32 s9, s81, 0
	s_add_u32 s10, s80, 0x29978500
	s_addc_u32 s11, s81, 0
	s_add_u32 s14, s80, 0x29978600
	s_addc_u32 s15, s81, 0
	s_add_u32 s16, s80, 0x29978700
	s_addc_u32 s17, s81, 0
	s_add_u32 s18, s80, 0x29978800
	s_addc_u32 s19, s81, 0
	s_add_u32 s20, s80, 0x29978900
	s_addc_u32 s21, s81, 0
	s_add_u32 s22, s80, 0x29978a00
	s_addc_u32 s23, s81, 0
	s_add_u32 s24, s80, 0x29978b00
	s_addc_u32 s25, s81, 0
	s_add_u32 s26, s80, 0x29978c00
	s_addc_u32 s27, s81, 0
	s_add_u32 s28, s80, 0x29978d00
	s_addc_u32 s29, s81, 0
	s_add_u32 s30, s80, 0x29978e00
	s_addc_u32 s31, s81, 0
	s_add_u32 s34, s80, 0x29978f00
	s_addc_u32 s35, s81, 0
	s_add_u32 s36, s80, 0x29979000
	s_addc_u32 s37, s81, 0
	s_add_u32 s38, s80, 0x29979100
	s_addc_u32 s39, s81, 0
	s_add_u32 s40, s80, 0x29979200
	s_addc_u32 s41, s81, 0
	s_add_u32 s42, s80, 0x29979300
	s_mul_i32 s33, s33, s76
	s_addc_u32 s43, s81, 0
	s_mov_b32 s50, 1
	v_mov_b32_e32 v16, 0
	s_branch .LBB0_1402
